# v28: P8 tail all loads up front (gate A fill unrolled, PLE/gate weight prefetch) + P5 tail fill unrolled with w_out prefetch
# baseline (speedup 1.0000x reference)
.LBB0_1432:
	v_mov_b32_e32 v2, 4
	v_lshlrev_b32_sdwa v2, v2, v0 dst_sel:DWORD dst_unused:UNUSED_PAD src0_sel:DWORD src1_sel:BYTE_0
	v_lshrrev_b32_e32 v6, 8, v0
	v_add_u32_e32 v4, 0, v2
	v_lshl_or_b32 v2, v6, 12, v2
	v_mov_b32_e32 v3, 0
	v_lshl_add_u64 v[2:3], s[82:83], 0, v[2:3]
	s_mov_b64 s[0:1], 0x25840000
	v_or_b32_e32 v5, 0xfffffe00, v0
	v_lshl_add_u64 v[2:3], v[2:3], 0, s[0:1]
	s_mov_b64 s[0:1], 0
	s_movk_i32 s4, 0x1040
	s_mov_b64 s[2:3], 0x2000
	s_movk_i32 s5, 0x5ff
	global_load_dwordx4 v[8:11], v[2:3], off
	v_lshl_add_u64 v[44:45], v[2:3], 0, s[2:3]
	global_load_dwordx4 v[12:15], v[44:45], off
	v_lshl_add_u64 v[44:45], v[44:45], 0, s[2:3]
	global_load_dwordx4 v[16:19], v[44:45], off
	v_lshl_add_u64 v[44:45], v[44:45], 0, s[2:3]
	global_load_dwordx4 v[20:23], v[44:45], off
	v_readlane_b32 s100, v254, 3
	v_and_b32_e32 v150, 15, v0
	v_and_b32_e32 v152, 48, v212
	v_mov_b32_e32 v153, 0
	v_mov_b32_e32 v151, 0
	s_and_b32 s100, s100, 0x7f
	v_lshl_or_b32 v150, s100, 4, v150
	s_lshl_b32 s100, s84, 9
	s_add_u32 s100, s82, s100
	s_addc_u32 s101, s83, 0
	v_lshl_add_u64 v[154:155], s[100:101], 0, v[152:153]
	s_mov_b64 s[100:101], 0x1a00000
	v_lshlrev_b64 v[156:157], 12, v[150:151]
	v_lshl_add_u64 v[154:155], v[154:155], 0, s[100:101]
	v_lshl_add_u64 v[154:155], v[154:155], 0, v[156:157]
	global_load_dwordx4 v[74:77], v[154:155], off
	global_load_dwordx4 v[78:81], v[154:155], off offset:64
	global_load_dwordx4 v[82:85], v[154:155], off offset:128
	global_load_dwordx4 v[86:89], v[154:155], off offset:192
	global_load_dwordx4 v[90:93], v[154:155], off offset:256
	global_load_dwordx4 v[94:97], v[154:155], off offset:320
	global_load_dwordx4 v[98:101], v[154:155], off offset:384
	global_load_dwordx4 v[102:105], v[154:155], off offset:448
	s_mov_b32 s99, 0
	s_waitcnt vmcnt(12) lgkmcnt(0)
	s_barrier
.LBB0_1433:
	v_mad_u32_u24 v7, v6, s4, v4
	s_waitcnt vmcnt(8)
	ds_write_b128 v7, v[8:11]
	ds_write_b128 v7, v[12:15] offset:8320
	ds_write_b128 v7, v[16:19] offset:16640
	ds_write_b128 v7, v[20:23] offset:24960
	s_or_b64 exec, exec, s[0:1]
	v_readlane_b32 s0, v254, 3
	s_cmpk_gt_i32 s0, 0x7f
	s_waitcnt lgkmcnt(0)
	s_barrier
	s_cbranch_scc1 .LBB0_1441
	s_add_u32 s4, s82, 0x25850000
	s_addc_u32 s5, s83, 0
	s_lshl_b32 s6, s84, 9
	s_add_u32 s0, s82, s6
	s_addc_u32 s1, s83, 0
	v_and_b32_e32 v2, 48, v212
	v_mov_b32_e32 v3, 0
	v_lshl_add_u64 v[4:5], s[0:1], 0, v[2:3]
	s_mov_b64 s[0:1], 0x1a00000
	v_and_b32_e32 v8, 0x70, v0
	v_lshl_add_u64 v[6:7], v[4:5], 0, s[0:1]
	v_and_b32_e32 v3, 7, v0
	s_movk_i32 s0, 0x1040
	v_or_b32_e32 v2, s6, v2
	v_lshlrev_b32_e32 v4, 4, v212
	v_lshlrev_b32_e32 v5, 2, v1
	v_lshlrev_b32_e32 v8, 2, v8
	s_add_i32 s6, s6, 0
	v_mad_u32_u24 v3, v3, s0, 0
	v_and_b32_e32 v4, 0x300, v4
	s_movk_i32 s2, 0x80
	v_add3_u32 v10, 0, v8, v5
	v_lshlrev_b32_e32 v8, 7, v0
	v_add_u32_e32 v5, s6, v5
	v_readlane_b32 s9, v254, 3
	v_readlane_b32 s6, v254, 2
	v_cmp_lt_u32_e32 vcc, 7, v1
	v_cmp_gt_u32_e64 s[0:1], 32, v212
	v_cmp_gt_u32_e64 s[2:3], s2, v0
	v_and_b32_e32 v11, 0x3800, v8
	v_lshl_add_u32 v8, s9, 4, v1
	s_lshl_b32 s8, s6, 4
	v_add_u32_e32 v1, v3, v2
	v_add_u32_e32 v12, v5, v4
	s_branch .LBB0_1437

.LBB0_1437:
	s_cmp_eq_u32 s99, 0
	s_cbranch_scc1 .Lp5t_w0
	v_ashrrev_i32_e32 v9, 31, v8
	v_lshlrev_b64 v[2:3], 12, v[8:9]
	v_lshl_add_u64 v[42:43], v[6:7], 0, v[2:3]
	global_load_dwordx4 v[2:5], v[42:43], off
	global_load_dwordx4 v[14:17], v[42:43], off offset:64
	global_load_dwordx4 v[18:21], v[42:43], off offset:128
	global_load_dwordx4 v[22:25], v[42:43], off offset:192
	global_load_dwordx4 v[26:29], v[42:43], off offset:256
	global_load_dwordx4 v[30:33], v[42:43], off offset:320
	global_load_dwordx4 v[34:37], v[42:43], off offset:384
	global_load_dwordx4 v[38:41], v[42:43], off offset:448
	s_branch .Lp5t_go

.Lp5t_go:
	s_add_i32 s99, s99, 1
	ds_read_b128 v[42:45], v1
	ds_read_b128 v[46:49], v1 offset:64
	ds_read_b128 v[50:53], v1 offset:128
	ds_read_b128 v[54:57], v1 offset:192
	ds_read_b128 v[58:61], v1 offset:256
	ds_read_b128 v[62:65], v1 offset:320
	ds_read_b128 v[66:69], v1 offset:384
	ds_read_b128 v[70:73], v1 offset:448
	s_waitcnt lgkmcnt(7)
	v_cndmask_b32_e64 v45, v45, 0, vcc
	v_cndmask_b32_e64 v44, v44, 0, vcc
	v_cndmask_b32_e64 v43, v43, 0, vcc
	v_cndmask_b32_e64 v42, v42, 0, vcc
	s_waitcnt lgkmcnt(6)
	v_cndmask_b32_e64 v49, v49, 0, vcc
	v_cndmask_b32_e64 v48, v48, 0, vcc
	v_cndmask_b32_e64 v47, v47, 0, vcc
	v_cndmask_b32_e64 v46, v46, 0, vcc
	s_waitcnt lgkmcnt(5)
	v_cndmask_b32_e64 v53, v53, 0, vcc
	v_cndmask_b32_e64 v52, v52, 0, vcc
	v_cndmask_b32_e64 v51, v51, 0, vcc
	v_cndmask_b32_e64 v50, v50, 0, vcc
	s_waitcnt lgkmcnt(4)
	v_cndmask_b32_e64 v57, v57, 0, vcc
	v_cndmask_b32_e64 v56, v56, 0, vcc
	v_cndmask_b32_e64 v55, v55, 0, vcc
	v_cndmask_b32_e64 v54, v54, 0, vcc
	s_waitcnt vmcnt(7)
	v_mfma_f32_16x16x32_bf16 v[2:5], v[42:45], v[2:5], 0
	s_waitcnt vmcnt(6)
	v_mfma_f32_16x16x32_bf16 v[2:5], v[46:49], v[14:17], v[2:5]
	s_waitcnt lgkmcnt(3)
	v_cndmask_b32_e64 v17, v61, 0, vcc
	v_cndmask_b32_e64 v16, v60, 0, vcc
	v_cndmask_b32_e64 v15, v59, 0, vcc
	s_waitcnt vmcnt(5)
	v_mfma_f32_16x16x32_bf16 v[2:5], v[50:53], v[18:21], v[2:5]
	v_cndmask_b32_e64 v14, v58, 0, vcc
	s_waitcnt lgkmcnt(2)
	v_cndmask_b32_e64 v21, v65, 0, vcc
	v_cndmask_b32_e64 v20, v64, 0, vcc
	s_waitcnt vmcnt(4)
	v_mfma_f32_16x16x32_bf16 v[2:5], v[54:57], v[22:25], v[2:5]
	v_cndmask_b32_e64 v19, v63, 0, vcc
	v_cndmask_b32_e64 v18, v62, 0, vcc
	s_waitcnt lgkmcnt(1)
	v_cndmask_b32_e64 v25, v69, 0, vcc
	s_waitcnt vmcnt(3)
	v_mfma_f32_16x16x32_bf16 v[2:5], v[14:17], v[26:29], v[2:5]
	v_cndmask_b32_e64 v24, v68, 0, vcc
	v_cndmask_b32_e64 v23, v67, 0, vcc
	v_cndmask_b32_e64 v22, v66, 0, vcc
	s_waitcnt vmcnt(2)
	v_mfma_f32_16x16x32_bf16 v[2:5], v[18:21], v[30:33], v[2:5]
	s_waitcnt lgkmcnt(0)
	v_cndmask_b32_e64 v17, v73, 0, vcc
	v_cndmask_b32_e64 v16, v72, 0, vcc
	v_cndmask_b32_e64 v15, v71, 0, vcc
	v_cndmask_b32_e64 v14, v70, 0, vcc
	s_waitcnt vmcnt(1)
	v_mfma_f32_16x16x32_bf16 v[2:5], v[22:25], v[34:37], v[2:5]
	s_waitcnt vmcnt(0)
	v_mfma_f32_16x16x32_bf16 v[2:5], v[14:17], v[38:41], v[2:5]
	s_and_saveexec_b64 s[6:7], s[0:1]
	s_cbranch_execz .LBB0_1439
	v_add_u32_e32 v9, 0x8000, v12
	s_nop 4
	ds_write2_b32 v9, v2, v3 offset0:128 offset1:144
	ds_write2_b32 v9, v4, v5 offset0:160 offset1:176

.LBB0_1721:
	s_movk_i32 s0, 0x200
	v_cmp_gt_u32_e32 vcc, s0, v0
	s_waitcnt vmcnt(4)
	v_lshlrev_b32_e32 v10, 3, v0
	v_readlane_b32 s10, v254, 15
	v_readlane_b32 s11, v254, 16
	v_lshlrev_b32_e32 v2, 4, v0
	v_lshlrev_b32_e32 v148, 4, v0
	v_mov_b32_e32 v149, 0
	s_mov_b64 s[98:99], 0x25880000
	v_lshl_add_u64 v[148:149], s[82:83], 0, v[148:149]
	v_readlane_b32 s100, v254, 3
	v_lshl_add_u64 v[148:149], v[148:149], 0, s[98:99]
	s_mov_b64 s[98:99], 0x2000
	s_nop 1
	global_load_dwordx4 v[2:5], v2, s[10:11]
	global_load_dwordx4 v[80:83], v[148:149], off
	v_lshl_add_u64 v[148:149], v[148:149], 0, s[98:99]
	global_load_dwordx4 v[84:87], v[148:149], off
	v_lshl_add_u64 v[148:149], v[148:149], 0, s[98:99]
	global_load_dwordx4 v[88:91], v[148:149], off
	v_lshl_add_u64 v[148:149], v[148:149], 0, s[98:99]
	global_load_dwordx4 v[92:95], v[148:149], off
	v_lshl_add_u64 v[148:149], v[148:149], 0, s[98:99]
	global_load_dwordx4 v[96:99], v[148:149], off
	v_lshl_add_u64 v[148:149], v[148:149], 0, s[98:99]
	global_load_dwordx4 v[100:103], v[148:149], off
	v_lshl_add_u64 v[148:149], v[148:149], 0, s[98:99]
	global_load_dwordx4 v[104:107], v[148:149], off
	v_lshl_add_u64 v[148:149], v[148:149], 0, s[98:99]
	global_load_dwordx4 v[108:111], v[148:149], off
	s_and_b32 s100, s100, 0x7f
	v_and_b32_e32 v152, 48, v212
	v_mov_b32_e32 v153, 0
	v_mov_b32_e32 v151, 0
	v_lshl_or_b32 v150, s100, 4, v1
	s_lshl_b32 s100, s84, 6
	s_add_u32 s100, s82, s100
	s_addc_u32 s101, s83, 0
	v_lshl_add_u64 v[154:155], s[100:101], 0, v[152:153]
	s_mov_b64 s[100:101], 0x6200000
	v_lshlrev_b64 v[156:157], 9, v[150:151]
	v_lshl_add_u64 v[154:155], v[154:155], 0, s[100:101]
	v_lshl_add_u64 v[154:155], v[154:155], 0, v[156:157]
	global_load_dwordx4 v[112:115], v[154:155], off
	s_lshl_b32 s100, s84, 9
	s_add_u32 s100, s82, s100
	s_addc_u32 s101, s83, 0
	v_lshl_add_u64 v[154:155], s[100:101], 0, v[152:153]
	s_mov_b64 s[100:101], 0x6400000
	v_lshlrev_b64 v[156:157], 12, v[150:151]
	v_lshl_add_u64 v[154:155], v[154:155], 0, s[100:101]
	v_lshl_add_u64 v[154:155], v[154:155], 0, v[156:157]
	global_load_dwordx4 v[116:119], v[154:155], off
	global_load_dwordx4 v[120:123], v[154:155], off offset:64
	global_load_dwordx4 v[124:127], v[154:155], off offset:128
	global_load_dwordx4 v[128:131], v[154:155], off offset:192
	global_load_dwordx4 v[132:135], v[154:155], off offset:256
	global_load_dwordx4 v[136:139], v[154:155], off offset:320
	global_load_dwordx4 v[140:143], v[154:155], off offset:384
	global_load_dwordx4 v[144:147], v[154:155], off offset:448
	s_mov_b32 s98, 0
	s_mov_b32 s99, 0
	s_waitcnt lgkmcnt(0)
	s_barrier
	s_and_saveexec_b64 s[0:1], vcc
	s_cbranch_execz .LBB0_1723
	v_readlane_b32 s4, v254, 9
	v_lshrrev_b32_e32 v6, 6, v0
	v_lshlrev_b32_e32 v7, 3, v0
	v_mul_u32_u24_e32 v6, 0x240, v6
	v_and_b32_e32 v7, 0x1f8, v7
	v_readlane_b32 s5, v254, 10
	v_readlane_b32 s6, v254, 11
	v_readlane_b32 s7, v254, 12
	v_readlane_b32 s8, v254, 13
	v_readlane_b32 s9, v254, 14
	v_readlane_b32 s12, v254, 17
	v_readlane_b32 s13, v254, 18
	v_readlane_b32 s14, v254, 19
	v_readlane_b32 s15, v254, 20
	v_readlane_b32 s16, v254, 21
	v_readlane_b32 s17, v254, 22
	v_readlane_b32 s18, v254, 23
	v_readlane_b32 s19, v254, 24
	s_waitcnt vmcnt(17)
	v_cvt_pk_bf16_f32 v2, v2, v3
	v_cvt_pk_bf16_f32 v3, v4, v5
	v_add3_u32 v4, 0, v6, v7
	ds_write_b64 v4, v[2:3]

.LBB0_1726:
	v_ashrrev_i32_e32 v9, 31, v8
	ds_read_b128 v[16:19], v13
	s_cmp_eq_u32 s98, 0
	s_cbranch_scc1 .Lp8t_pw0
	v_lshlrev_b64 v[2:3], 9, v[8:9]
	v_lshl_add_u64 v[2:3], v[6:7], 0, v[2:3]
	global_load_dwordx4 v[2:5], v[2:3], off
	s_waitcnt vmcnt(0)
	s_branch .Lp8t_pgo
.Lp8t_pw0:
	s_waitcnt vmcnt(8)
	v_mov_b64_e32 v[2:3], v[112:113]
	v_mov_b64_e32 v[4:5], v[114:115]
.Lp8t_pgo:
	s_add_i32 s98, s98, 1
	s_waitcnt lgkmcnt(0)
	v_cndmask_b32_e64 v19, v19, 0, vcc
	v_cndmask_b32_e64 v18, v18, 0, vcc
	v_cndmask_b32_e64 v17, v17, 0, vcc
	v_cndmask_b32_e64 v16, v16, 0, vcc
	s_nop 1
	v_mfma_f32_16x16x32_bf16 v[2:5], v[16:19], v[2:5], 0
	s_and_saveexec_b64 s[8:9], s[0:1]
	s_cbranch_execz .LBB0_1728
	s_nop 5
	ds_write2_b32 v14, v2, v3 offset0:128 offset1:144
	ds_write2_b32 v14, v4, v5 offset0:160 offset1:176

.LBB0_1730:
	s_mov_b64 s[0:1], 0
	v_and_b32_e32 v7, 0xff8, v10
	s_barrier
.LBB0_1731:
	s_waitcnt vmcnt(9)
	v_add_u32_e32 v2, 0, v7
	v_cvt_pk_bf16_f32 v80, v80, v81
	v_cvt_pk_bf16_f32 v81, v82, v83
	ds_write_b64 v2, v[80:81]
	v_cvt_pk_bf16_f32 v84, v84, v85
	v_cvt_pk_bf16_f32 v85, v86, v87
	ds_write_b64 v2, v[84:85] offset:4160
	v_cvt_pk_bf16_f32 v88, v88, v89
	v_cvt_pk_bf16_f32 v89, v90, v91
	ds_write_b64 v2, v[88:89] offset:8320
	v_cvt_pk_bf16_f32 v92, v92, v93
	v_cvt_pk_bf16_f32 v93, v94, v95
	ds_write_b64 v2, v[92:93] offset:12480
	v_cvt_pk_bf16_f32 v96, v96, v97
	v_cvt_pk_bf16_f32 v97, v98, v99
	ds_write_b64 v2, v[96:97] offset:16640
	v_cvt_pk_bf16_f32 v100, v100, v101
	v_cvt_pk_bf16_f32 v101, v102, v103
	ds_write_b64 v2, v[100:101] offset:20800
	v_cvt_pk_bf16_f32 v104, v104, v105
	v_cvt_pk_bf16_f32 v105, v106, v107
	ds_write_b64 v2, v[104:105] offset:24960
	v_cvt_pk_bf16_f32 v108, v108, v109
	v_cvt_pk_bf16_f32 v109, v110, v111
	ds_write_b64 v2, v[108:109] offset:29120
	s_or_b64 exec, exec, s[0:1]
	s_andn2_b64 vcc, exec, s[4:5]
	s_waitcnt lgkmcnt(0)
	s_barrier
	s_cbranch_vccnz .LBB0_1739
	s_add_u32 s4, s82, 0x258a0000
	s_addc_u32 s5, s83, 0
	s_lshl_b32 s6, s84, 9
	s_add_u32 s0, s82, s6
	s_addc_u32 s1, s83, 0
	v_and_b32_e32 v2, 48, v212
	v_mov_b32_e32 v3, 0
	v_lshl_add_u64 v[4:5], s[0:1], 0, v[2:3]
	s_mov_b64 s[0:1], 0x6400000
	v_and_b32_e32 v8, 0x70, v0
	v_lshl_add_u64 v[6:7], v[4:5], 0, s[0:1]
	v_and_b32_e32 v3, 7, v0
	s_movk_i32 s0, 0x1040
	v_or_b32_e32 v2, s6, v2
	v_lshlrev_b32_e32 v4, 4, v212
	v_lshlrev_b32_e32 v5, 2, v1
	v_lshlrev_b32_e32 v8, 2, v8
	s_add_i32 s6, s6, 0
	v_mad_u32_u24 v3, v3, s0, 0
	v_and_b32_e32 v4, 0x300, v4
	s_movk_i32 s2, 0x80
	v_add3_u32 v10, 0, v8, v5
	v_lshlrev_b32_e32 v8, 7, v0
	v_add_u32_e32 v5, s6, v5
	v_readlane_b32 s9, v254, 3
	v_readlane_b32 s6, v254, 2
	v_cmp_lt_u32_e32 vcc, 7, v1
	v_cmp_gt_u32_e64 s[0:1], 32, v212
	v_cmp_gt_u32_e64 s[2:3], s2, v0
	v_and_b32_e32 v11, 0x3800, v8
	v_lshl_or_b32 v8, s9, 4, v1
	s_lshl_b32 s8, s6, 4
	v_add_u32_e32 v1, v3, v2
	v_add_u32_e32 v12, v5, v4
	s_branch .LBB0_1735

.Lp8t_gw0:
	s_waitcnt vmcnt(0)
	v_mov_b64_e32 v[2:3], v[116:117]
	v_mov_b64_e32 v[4:5], v[118:119]
	v_mov_b64_e32 v[14:15], v[120:121]
	v_mov_b64_e32 v[16:17], v[122:123]
	v_mov_b64_e32 v[18:19], v[124:125]
	v_mov_b64_e32 v[20:21], v[126:127]
	v_mov_b64_e32 v[22:23], v[128:129]
	v_mov_b64_e32 v[24:25], v[130:131]
	v_mov_b64_e32 v[26:27], v[132:133]
	v_mov_b64_e32 v[28:29], v[134:135]
	v_mov_b64_e32 v[30:31], v[136:137]
	v_mov_b64_e32 v[32:33], v[138:139]
	v_mov_b64_e32 v[34:35], v[140:141]
	v_mov_b64_e32 v[36:37], v[142:143]
	v_mov_b64_e32 v[38:39], v[144:145]
	v_mov_b64_e32 v[40:41], v[146:147]
